# mixer work queue: each workgroup's first item pair is static (slot = blockIdx), later fetches use the device counter + gridDim
# speedup vs baseline: 1.0034x; 1.0032x over previous
.LBB0_127:
	v_readlane_b32 s0, v255, 40
	v_readlane_b32 s1, v255, 41
	s_mov_b32 s6, s0
	s_lshl_b32 s0, s0, 2
	v_readlane_b32 s1, v254, 41
	s_add_u32 s66, s1, s0
	v_readlane_b32 s0, v254, 42
	s_addc_u32 s67, s0, 0
	s_lshl_b32 s0, s6, 2
	v_writelane_b32 v255, s0, 47
	s_lshl_b32 s0, s6, 1
	s_mov_b32 s1, s21
	v_writelane_b32 v255, s0, 48
	s_lshl_b32 s20, s6, 7
	v_readlane_b32 s36, v254, 53
	v_writelane_b32 v255, s1, 49
	s_lshl_b32 s0, s6, 3
	v_writelane_b32 v255, s0, 50
	s_lshl_b64 s[0:1], s[20:21], 2
	v_readlane_b32 s48, v255, 1
	v_readlane_b32 s49, v255, 2
	s_add_u32 s0, s48, s0
	s_addc_u32 s1, s49, s1
	v_readlane_b32 s47, v255, 0
	v_readlane_b32 s50, v255, 3
	v_readlane_b32 s51, v255, 4
	v_writelane_b32 v255, s0, 51
	v_mov_b32_e32 v0, v137
	v_readlane_b32 s37, v254, 54
	v_writelane_b32 v255, s1, 52
	v_readfirstlane_b32 s0, v0
	v_cmp_eq_u32_e64 s[62:63], 0, v0
	s_ashr_i32 s9, s0, 8
	v_and_b32_e32 v161, 63, v0
	v_writelane_b32 v255, s62, 53
	v_bfe_u32 v201, v0, 6, 2
	s_mul_i32 s11, s9, 0x12000
	v_writelane_b32 v255, s63, 54
	v_readlane_b32 s38, v254, 55
	v_readlane_b32 s39, v254, 56
	v_readlane_b32 s40, v254, 57
	v_readlane_b32 s41, v254, 58
	v_readlane_b32 s42, v254, 59
	v_readlane_b32 s43, v254, 60
	v_readlane_b32 s44, v254, 61
	v_readlane_b32 s45, v254, 62
	v_readlane_b32 s46, v254, 63
	v_readlane_b32 s0, v255, 33
	v_readlane_b32 s1, v255, 34
	s_nop 4
	s_load_dword s0, s[0:1], 0x0
	s_waitcnt lgkmcnt(0)
	s_nop 0
	v_writelane_b32 v255, s0, 57
	s_mov_b32 s0, 1
	s_nop 0
	v_writelane_b32 v255, s0, 58
	s_branch .LBB0_130

.LBB0_130:
	s_waitcnt vmcnt(0) lgkmcnt(0)
	s_barrier
	s_and_saveexec_b64 s[0:1], s[62:63]
	s_cbranch_execz .LBB0_134
	s_mov_b64 s[26:27], exec
	v_mbcnt_lo_u32_b32 v0, s26, 0
	v_mbcnt_hi_u32_b32 v0, s27, v0
	v_cmp_eq_u32_e32 vcc, 0, v0
	s_and_saveexec_b64 s[22:23], vcc
	s_cbranch_execz .LBB0_133
	v_readlane_b32 s6, v255, 58
	s_cmp_lg_u32 s6, 0
	s_cbranch_scc0 .Lmixq_dyn
	v_readlane_b32 s6, v253, 0
	v_mov_b32_e32 v2, s6
	s_branch .LBB0_133
.Lmixq_dyn:
	s_bcnt1_i32_b64 s6, s[26:27]
	v_mov_b32_e32 v2, s6
	global_atomic_add v2, v1, v2, s[66:67] sc0
	v_readlane_b32 s6, v255, 57
	s_waitcnt vmcnt(0)
	v_add_u32_e32 v2, s6, v2

.LBB0_134:
	s_or_b64 exec, exec, s[0:1]
	s_mov_b32 s0, 0
	s_nop 0
	v_writelane_b32 v255, s0, 58
	s_mov_b64 s[0:1], src_shared_base
	v_mov_b32_e32 v163, s1
	s_waitcnt lgkmcnt(0)
	s_barrier
	flat_load_dword v0, v[162:163] sc0 sc1
	s_waitcnt vmcnt(0)
	s_mov_b64 s[0:1], -1
	s_waitcnt lgkmcnt(0)
	v_lshl_add_u32 v0, v0, 1, s9
	s_nop 0
	v_readfirstlane_b32 s12, v0
	s_cmpk_gt_i32 s12, 0x57f
	s_cbranch_scc1 .LBB0_129
	s_cmpk_gt_i32 s12, 0xff
	s_cbranch_scc0 .LBB0_318
	s_cmpk_gt_u32 s12, 0x17f
	s_cbranch_scc0 .LBB0_288
	s_cmpk_gt_u32 s12, 0x1ff
	s_cbranch_scc0 .LBB0_277
	s_cmpk_gt_u32 s12, 0x27f
	s_cbranch_scc0 .LBB0_220
	s_cmpk_gt_u32 s12, 0x37f
	s_cbranch_scc0 .LBB0_199
	s_cmpk_gt_u32 s12, 0x47f
	s_cbranch_scc0 .LBB0_156
	s_mov_b64 s[0:1], 0
	s_add_u32 s0, s94, s0
	s_addc_u32 s1, s95, s1
	s_mov_b64 s[22:23], 0
	s_lshl_b32 s6, s12, 4
	s_and_b32 s13, s6, 0x7fffff00
	s_add_i32 s22, s13, 0xffffb800
	s_add_u32 s26, s0, 0x8748000
	s_addc_u32 s27, s1, 0
	s_lshl_b32 s13, s12, 6
	v_mov_b32_e32 v22, v161
	s_and_b32 s13, s13, 0xc0
	v_readfirstlane_b32 s8, v201
	v_and_b32_e32 v26, 15, v22
	s_or_b32 s13, s13, s22
	s_lshl_b32 s36, s8, 4
	v_or_b32_e32 v0, s13, v26
	v_ashrrev_i32_e32 v53, 4, v22
	v_add_u32_e32 v50, s36, v0
	v_mov_b64_e32 v[2:3], s[26:27]
	s_movk_i32 s13, 0x1a20
	s_and_b32 s14, s6, 0xc0
	v_mad_i64_i32 v[2:3], s[34:35], v50, s13, v[2:3]
	s_lshl_b32 s20, s14, 1
	v_lshlrev_b32_e32 v4, 3, v53
	v_lshl_add_u64 v[2:3], v[2:3], 0, s[20:21]
	v_ashrrev_i32_e32 v5, 31, v4
	v_lshl_add_u64 v[2:3], v[4:5], 1, v[2:3]
	global_load_dwordx4 v[6:9], v[2:3], off offset:3072
	s_nop 0
	global_load_dwordx4 v[2:5], v[2:3], off offset:3136
	s_mul_i32 s13, s22, 0x1a20
	s_mul_hi_u32 s6, s22, 0x1a20
	s_add_u32 s13, s26, s13
	s_addc_u32 s6, s27, s6
	s_add_u32 s38, s13, s20
	s_addc_u32 s39, s6, 0
	s_mov_b32 s23, s21
	s_add_u32 s6, s38, 0xe00
	s_addc_u32 s13, s39, 0
	s_lshl_b64 s[22:23], s[22:23], 9
	v_ashrrev_i32_e32 v12, 3, v22
	s_add_u32 s19, s0, s22
	v_add_u32_e32 v0, s36, v12
	s_addc_u32 s22, s1, s23
	s_lshl_b32 s14, s14, 6
	v_and_b32_e32 v13, 2, v12
	v_lshrrev_b32_e32 v10, 1, v0
	s_add_u32 s44, s19, s14
	v_and_or_b32 v10, v10, 12, v13
	s_movk_i32 s16, 0xd10
	s_addc_u32 s49, s22, 0
	v_lshrrev_b32_e32 v10, 1, v10
	v_mad_i64_i32 v[46:47], s[22:23], v0, s16, 0
	s_add_u32 s14, s44, 0xb478000
	v_bitop3_b32 v58, v10, v22, 7 bitop3:0x78
	v_lshlrev_b64 v[34:35], 1, v[46:47]
	s_addc_u32 s19, s49, 0
	v_lshl_add_u64 v[10:11], s[38:39], 0, v[34:35]
	v_lshlrev_b32_e32 v0, 4, v58
	s_lshl_b32 s22, s8, 11
	s_lshl_b32 s26, s8, 1
	v_lshl_add_u64 v[10:11], v[10:11], 0, v[0:1]
	s_mov_b64 s[34:35], 0xe00
	s_add_i32 s48, s11, s22
	v_lshl_add_u64 v[10:11], v[10:11], 0, s[34:35]
	s_mov_b32 m0, s48
	s_or_b32 s37, s26, 1
	s_barrier
	global_load_lds_dwordx4 v[10:11], off
	v_lshl_add_u32 v10, s37, 3, v12
	v_lshrrev_b32_e32 v11, 1, v10
	v_and_or_b32 v11, v11, 12, v13
	v_mad_i64_i32 v[48:49], s[22:23], v10, s16, 0
	v_lshrrev_b32_e32 v11, 1, v11
	s_lshl_b32 s22, s37, 10
	v_bitop3_b32 v60, v11, v22, 7 bitop3:0x78
	v_lshlrev_b64 v[36:37], 1, v[48:49]
	s_add_i32 s45, s11, s22
	s_lshr_b32 s22, s8, 31
	v_lshl_add_u64 v[10:11], s[38:39], 0, v[36:37]
	v_lshlrev_b32_e32 v38, 4, v60
	v_mov_b32_e32 v39, v1
	s_add_i32 s22, s8, s22
	s_bfe_i32 s8, s8, 0x1001e
	v_lshl_add_u64 v[10:11], v[10:11], 0, v[38:39]
	s_lshr_b32 s8, s8, 30
	v_lshl_add_u64 v[10:11], v[10:11], 0, s[34:35]
	s_ashr_i32 s34, s22, 1
	s_add_i32 s22, s26, s8
	s_and_b32 s22, s22, 0x7ffffc
	s_ashr_i32 s35, s34, 31
	s_sub_i32 s22, s26, s22
	s_lshl_b64 s[40:41], s[34:35], 14
	s_add_u32 s26, s14, s40
	s_addc_u32 s27, s19, s41
	s_lshl_b32 s22, s22, 9
	s_ashr_i32 s23, s22, 31
	s_lshl_b64 s[22:23], s[22:23], 1
	s_add_u32 s26, s26, s22
	s_addc_u32 s27, s27, s23
	s_add_i32 s8, s37, s8
	s_mov_b32 m0, s45
	s_ashr_i32 s36, s8, 2
	s_and_b32 s8, s8, 0x7ffffc
	global_load_lds_dwordx4 v[10:11], off
	v_lshlrev_b32_e32 v10, 3, v22
	s_sub_i32 s8, s37, s8
	s_ashr_i32 s37, s36, 31
	v_ashrrev_i32_e32 v11, 31, v10
	s_add_i32 s46, s48, 0x2000
	s_lshl_b64 s[42:43], s[36:37], 14
	v_lshlrev_b64 v[56:57], 1, v[10:11]
	s_add_u32 s47, s14, s42
	v_lshl_add_u64 v[10:11], s[26:27], 0, v[56:57]
	s_addc_u32 s53, s19, s43
	s_lshl_b32 s26, s8, 9
	s_ashr_i32 s27, s26, 31
	s_lshl_b64 s[26:27], s[26:27], 1
	s_add_u32 s52, s47, s26
	s_mov_b32 m0, s46
	s_addc_u32 s53, s53, s27
	s_add_i32 s47, s45, 0x2000
	global_load_lds_dwordx4 v[10:11], off
	v_lshl_add_u64 v[10:11], s[52:53], 0, v[56:57]
	s_mov_b32 m0, s47
	v_lshrrev_b32_e32 v14, 1, v22
	global_load_lds_dwordx4 v[10:11], off
	v_lshlrev_b32_e32 v10, 1, v22
	v_and_b32_e32 v11, 3, v22
	v_and_or_b32 v10, v10, 24, v11
	v_bitop3_b32 v11, v14, v53, 7 bitop3:0x6c
	v_add_u32_e32 v16, 4, v53
	v_lshlrev_b32_e32 v11, 4, v11
	v_lshl_add_u32 v15, v10, 7, s11
	v_bitop3_b32 v14, v14, v16, 7 bitop3:0x6c
	v_add_u32_e32 v70, v15, v11
	v_lshlrev_b32_e32 v14, 4, v14
	s_waitcnt vmcnt(0)
	s_waitcnt vmcnt(0) lgkmcnt(0)
	s_barrier
	ds_read_b128 v[10:13], v70
	v_add_u32_e32 v71, v15, v14
	ds_read_b128 v[14:17], v70 offset:512
	ds_read_b128 v[18:21], v71
	v_and_b32_e32 v27, -16, v22
	ds_read_b128 v[22:25], v71 offset:512
	s_waitcnt lgkmcnt(3)
	v_mfma_f32_16x16x32_bf16 v[10:13], v[10:13], v[6:9], 0
	s_mov_b32 s8, 0xff800000
	s_waitcnt lgkmcnt(2)
	v_mfma_f32_16x16x32_bf16 v[14:17], v[14:17], v[6:9], 0
	s_waitcnt lgkmcnt(1)
	v_mfma_f32_16x16x32_bf16 v[10:13], v[18:21], v[2:5], v[10:13]
	v_lshlrev_b32_e32 v18, 6, v26
	v_add_u32_e32 v19, s11, v27
	v_add_u32_e32 v51, v19, v18
	s_waitcnt lgkmcnt(0)
	v_mfma_f32_16x16x32_bf16 v[14:17], v[22:25], v[2:5], v[14:17]
	ds_read_b128 v[18:21], v51 offset:8192
	ds_read_b128 v[26:29], v51 offset:9216
	ds_read_b128 v[30:33], v51 offset:10240
	ds_read_b128 v[76:79], v51 offset:11264
	v_mul_f32_e32 v22, 0x3e38aa3b, v10
	v_mul_f32_e32 v24, 0x3e38aa3b, v11
	v_mul_f32_e32 v40, 0x3e38aa3b, v12
	s_nop 0
	v_mul_f32_e32 v41, 0x3e38aa3b, v16
	v_mul_f32_e32 v42, 0x3e38aa3b, v13
	v_mul_f32_e32 v43, 0x3e38aa3b, v17
	v_mul_f32_e32 v23, 0x3e38aa3b, v14
	v_mul_f32_e32 v25, 0x3e38aa3b, v15
	v_max_f32_e32 v22, v22, v24
	v_max_f32_e32 v24, v40, v42
	v_max_f32_e32 v40, v41, v43
	v_max3_f32 v23, v23, v25, v40
	v_max3_f32 v22, v22, v24, v23
	v_mov_b32_e32 v23, v22
	s_nop 1
	v_permlane16_swap_b32_e32 v22, v23
	v_max_f32_e32 v23, v23, v23
	v_max_f32_e32 v22, v22, v22
	v_max_f32_e32 v22, v22, v23
	v_mov_b32_e32 v23, v22
	s_nop 1
	v_permlane32_swap_b32_e32 v22, v23
	v_max3_f32 v52, v22, v23, s8
	s_mov_b32 s8, 0x3e38aa3b
	v_sub_f32_e32 v22, 0xff800000, v52
	v_fma_f32 v10, v10, s8, -v52
	v_exp_f32_e32 v55, v10
	v_fma_f32 v10, v11, s8, -v52
	v_exp_f32_e32 v11, v22
	v_exp_f32_e32 v59, v10
	v_fma_f32 v10, v12, s8, -v52
	v_exp_f32_e32 v61, v10
	v_fma_f32 v10, v13, s8, -v52
	v_cmp_neq_f32_e32 vcc, 1.0, v11
	v_exp_f32_e32 v64, v10
	v_fma_f32 v10, v14, s8, -v52
	s_cmp_lg_u64 vcc, 0
	v_exp_f32_e32 v65, v10
	v_fma_f32 v10, v15, s8, -v52
	v_mul_f32_e32 v68, 0, v11
	s_cselect_b64 vcc, -1, 0
	s_add_u32 s38, s38, 0x69600
	v_exp_f32_e32 v66, v10
	v_fma_f32 v10, v16, s8, -v52
	v_cndmask_b32_e32 v80, 0, v68, vcc
	s_addc_u32 s39, s39, 0
	v_exp_f32_e32 v67, v10
	v_fma_f32 v10, v17, s8, -v52
	v_mov_b32_e32 v81, v80
	v_mov_b32_e32 v82, v80
	v_mov_b32_e32 v83, v80
	s_add_u32 s8, s44, 0xb480000
	v_exp_f32_e32 v69, v10
	s_nop 1
	v_cvt_pk_bf16_f32 v84, v55, v59
	v_cvt_pk_bf16_f32 v85, v61, v64
	v_cvt_pk_bf16_f32 v86, v65, v66
	v_cvt_pk_bf16_f32 v87, v67, v69
	s_nop 1
	s_addc_u32 s49, s49, 0
	s_waitcnt lgkmcnt(3)
	v_mfma_f32_16x16x32_bf16 v[14:17], v[18:21], v[84:87], v[80:83]
	v_lshl_add_u64 v[18:19], s[38:39], 0, v[34:35]
	s_add_i32 s44, s48, 0x4000
	v_lshl_add_u64 v[18:19], v[18:19], 0, v[0:1]
	s_mov_b32 m0, s44
	s_waitcnt lgkmcnt(2)
	v_mfma_f32_16x16x32_bf16 v[10:13], v[26:29], v[84:87], v[80:83]
	global_load_lds_dwordx4 v[18:19], off
	v_lshl_add_u64 v[18:19], s[38:39], 0, v[36:37]
	s_add_i32 s38, s45, 0x4000
	s_add_u32 s39, s8, s40
	s_addc_u32 s41, s49, s41
	s_add_u32 s40, s39, s22
	s_addc_u32 s41, s41, s23
	s_add_i32 s39, s48, 0x6000
	v_lshl_add_u64 v[18:19], v[18:19], 0, v[38:39]
	s_mov_b32 m0, s38
	s_add_u32 s8, s8, s42
	global_load_lds_dwordx4 v[18:19], off
	v_lshl_add_u64 v[18:19], s[40:41], 0, v[56:57]
	s_addc_u32 s41, s49, s43
	s_add_u32 s40, s8, s26
	s_mov_b32 m0, s39
	s_addc_u32 s41, s41, s27
	global_load_lds_dwordx4 v[18:19], off
	v_lshl_add_u64 v[18:19], s[40:41], 0, v[56:57]
	s_add_i32 s40, s45, 0x6000
	s_mov_b32 m0, s40
	s_waitcnt lgkmcnt(0)
	v_mfma_f32_16x16x32_bf16 v[34:37], v[30:33], v[84:87], v[80:83]
	global_load_lds_dwordx4 v[18:19], off
	ds_read_b128 v[18:21], v70 offset:4096
	ds_read_b128 v[22:25], v70 offset:4608
	ds_read_b128 v[26:29], v71 offset:4096
	ds_read_b128 v[30:33], v71 offset:4608
	s_waitcnt lgkmcnt(0)
	v_mfma_f32_16x16x32_bf16 v[38:41], v[22:25], v[6:9], 0
	v_mfma_f32_16x16x32_bf16 v[18:21], v[18:21], v[6:9], 0
	v_mfma_f32_16x16x32_bf16 v[30:33], v[30:33], v[2:5], v[38:41]
	v_mfma_f32_16x16x32_bf16 v[18:21], v[26:29], v[2:5], v[18:21]
	ds_read_b128 v[22:25], v51 offset:12288
	ds_read_b128 v[26:29], v51 offset:13312
	s_nop 4
	v_mul_f32_e32 v44, 0x3e38aa3b, v32
	v_mul_f32_e32 v45, 0x3e38aa3b, v33
	v_mul_f32_e32 v42, 0x3e38aa3b, v30
	v_mul_f32_e32 v54, 0x3e38aa3b, v18
	v_mul_f32_e32 v62, 0x3e38aa3b, v19
	v_mul_f32_e32 v43, 0x3e38aa3b, v31
	v_mul_f32_e32 v63, 0x3e38aa3b, v20
	v_mul_f32_e32 v75, 0x3e38aa3b, v21
	v_max_f32_e32 v19, v44, v45
	v_max_f32_e32 v0, v54, v62
	v_max_f32_e32 v18, v63, v75
	v_max3_f32 v19, v42, v43, v19
	v_max3_f32 v0, v0, v18, v19
	v_mov_b32_e32 v18, v0
	s_nop 1
	v_permlane16_swap_b32_e32 v0, v18
	v_max_f32_e32 v18, v18, v18
	v_max_f32_e32 v0, v0, v0
	v_max_f32_e32 v0, v0, v18
	v_mov_b32_e32 v18, v0
	s_nop 1
	v_permlane32_swap_b32_e32 v0, v18
	v_max3_f32 v0, v52, v0, v18
	v_sub_f32_e32 v18, v52, v0
	v_exp_f32_e32 v52, v18
	ds_read_b128 v[38:41], v51 offset:14336
	ds_read_b128 v[18:21], v51 offset:15360
	v_mfma_f32_16x16x32_bf16 v[30:33], v[76:79], v[84:87], v[80:83]
	v_cmp_neq_f32_e32 vcc, 1.0, v52
	s_cbranch_vccz .LBB0_143
	v_pk_mul_f32 v[16:17], v[16:17], v[52:53] op_sel_hi:[1,0]
	v_pk_mul_f32 v[14:15], v[14:15], v[52:53] op_sel_hi:[1,0]
	v_pk_mul_f32 v[12:13], v[12:13], v[52:53] op_sel_hi:[1,0]
	v_pk_mul_f32 v[10:11], v[10:11], v[52:53] op_sel_hi:[1,0]
	v_pk_mul_f32 v[36:37], v[36:37], v[52:53] op_sel_hi:[1,0]
	v_pk_mul_f32 v[34:35], v[34:35], v[52:53] op_sel_hi:[1,0]
	v_pk_mul_f32 v[32:33], v[32:33], v[52:53] op_sel_hi:[1,0]
	v_pk_mul_f32 v[30:31], v[30:31], v[52:53] op_sel_hi:[1,0]
